# uvscan GEMM epilogue: z loads batched (16 in flight) instead of load-wait-store per step
# speedup vs baseline: 1.0105x; 1.0105x over previous
.LBB0_209:
	v_ashrrev_i32_e32 v165, 6, v130
	v_mad_u32_u24 v164, v165, s33, v0
	v_add_u32_e32 v165, s0, v165
	v_mad_i64_i32 v[86:87], s[18:19], v165, s96, v[66:67]
	s_mov_b32 s18, 0x1c000
	s_mov_b32 s19, 0
	global_load_dwordx2 v[132:133], v[86:87], off offset:1024
	v_lshl_add_u64 v[86:87], v[86:87], 0, s[18:19]
	global_load_dwordx2 v[134:135], v[86:87], off offset:1024
	v_lshl_add_u64 v[86:87], v[86:87], 0, s[18:19]
	global_load_dwordx2 v[136:137], v[86:87], off offset:1024
	v_lshl_add_u64 v[86:87], v[86:87], 0, s[18:19]
	global_load_dwordx2 v[138:139], v[86:87], off offset:1024
	v_lshl_add_u64 v[86:87], v[86:87], 0, s[18:19]
	global_load_dwordx2 v[140:141], v[86:87], off offset:1024
	v_lshl_add_u64 v[86:87], v[86:87], 0, s[18:19]
	global_load_dwordx2 v[142:143], v[86:87], off offset:1024
	v_lshl_add_u64 v[86:87], v[86:87], 0, s[18:19]
	global_load_dwordx2 v[144:145], v[86:87], off offset:1024
	v_lshl_add_u64 v[86:87], v[86:87], 0, s[18:19]
	global_load_dwordx2 v[146:147], v[86:87], off offset:1024
	v_lshl_add_u64 v[86:87], v[86:87], 0, s[18:19]
	global_load_dwordx2 v[148:149], v[86:87], off offset:1024
	v_lshl_add_u64 v[86:87], v[86:87], 0, s[18:19]
	global_load_dwordx2 v[150:151], v[86:87], off offset:1024
	v_lshl_add_u64 v[86:87], v[86:87], 0, s[18:19]
	global_load_dwordx2 v[152:153], v[86:87], off offset:1024
	v_lshl_add_u64 v[86:87], v[86:87], 0, s[18:19]
	global_load_dwordx2 v[154:155], v[86:87], off offset:1024
	v_lshl_add_u64 v[86:87], v[86:87], 0, s[18:19]
	global_load_dwordx2 v[156:157], v[86:87], off offset:1024
	v_lshl_add_u64 v[86:87], v[86:87], 0, s[18:19]
	global_load_dwordx2 v[158:159], v[86:87], off offset:1024
	v_lshl_add_u64 v[86:87], v[86:87], 0, s[18:19]
	global_load_dwordx2 v[160:161], v[86:87], off offset:1024
	v_lshl_add_u64 v[86:87], v[86:87], 0, s[18:19]
	global_load_dwordx2 v[162:163], v[86:87], off offset:1024
	v_lshl_add_u64 v[86:87], v[86:87], 0, s[18:19]
	s_mov_b32 s18, 0xffe40000
	s_mov_b32 s19, -1
	v_lshl_add_u64 v[86:87], v[86:87], 0, s[18:19]
	s_mov_b32 s18, 0x1c000
	s_mov_b32 s19, 0
	ds_read_b128 v[172:175], v164
	ds_read_b128 v[176:179], v164 offset:8320
	ds_read_b128 v[180:183], v164 offset:16640
	ds_read_b128 v[184:187], v164 offset:24960
	v_add_u32_e32 v164, 0x8200, v164
	s_waitcnt vmcnt(15) lgkmcnt(3)
	v_lshlrev_b32_e32 v92, 16, v132
	v_and_b32_e32 v132, 0xffff0000, v132
	v_mul_f32_e32 v90, 0xbfb8aa3b, v92
	v_mul_f32_e32 v91, 0xbfb8aa3b, v132
	v_exp_f32_e32 v90, v90
	v_exp_f32_e32 v91, v91
	s_nop 0
	v_pk_add_f32 v[90:91], v[90:91], 1.0 op_sel_hi:[1,0]
	s_nop 0
	v_rcp_f32_e32 v94, v91
	s_nop 0
	v_mul_f32_e32 v91, v132, v94
	v_rcp_f32_e32 v93, v90
	s_nop 0
	v_mul_f32_e32 v90, v92, v93
	v_pk_mul_f32 v[172:173], v[172:173], v[90:91]
	v_lshlrev_b32_e32 v90, 16, v133
	v_and_b32_e32 v91, 0xffff0000, v133
	v_mul_f32_e32 v132, 0xbfb8aa3b, v90
	v_mul_f32_e32 v133, 0xbfb8aa3b, v91
	v_exp_f32_e32 v132, v132
	v_exp_f32_e32 v133, v133
	v_cvt_pk_bf16_f32 v172, v172, v173
	v_pk_add_f32 v[132:133], v[132:133], 1.0 op_sel_hi:[1,0]
	s_nop 0
	v_rcp_f32_e32 v93, v133
	s_nop 0
	v_mul_f32_e32 v133, v91, v93
	v_rcp_f32_e32 v92, v132
	s_nop 0
	v_mul_f32_e32 v132, v90, v92
	v_pk_mul_f32 v[174:175], v[174:175], v[132:133]
	s_nop 0
	v_cvt_pk_bf16_f32 v173, v174, v175
	global_store_dwordx2 v[86:87], v[172:173], off offset:2048
	v_lshl_add_u64 v[86:87], v[86:87], 0, s[18:19]
	s_waitcnt vmcnt(15) lgkmcnt(2)
	v_lshlrev_b32_e32 v92, 16, v134
	v_and_b32_e32 v134, 0xffff0000, v134
	v_mul_f32_e32 v90, 0xbfb8aa3b, v92
	v_mul_f32_e32 v91, 0xbfb8aa3b, v134
	v_exp_f32_e32 v90, v90
	v_exp_f32_e32 v91, v91
	s_nop 0
	v_pk_add_f32 v[90:91], v[90:91], 1.0 op_sel_hi:[1,0]
	s_nop 0
	v_rcp_f32_e32 v94, v91
	s_nop 0
	v_mul_f32_e32 v91, v134, v94
	v_rcp_f32_e32 v93, v90
	s_nop 0
	v_mul_f32_e32 v90, v92, v93
	v_pk_mul_f32 v[176:177], v[176:177], v[90:91]
	v_lshlrev_b32_e32 v90, 16, v135
	v_and_b32_e32 v91, 0xffff0000, v135
	v_mul_f32_e32 v134, 0xbfb8aa3b, v90
	v_mul_f32_e32 v135, 0xbfb8aa3b, v91
	v_exp_f32_e32 v134, v134
	v_exp_f32_e32 v135, v135
	v_cvt_pk_bf16_f32 v176, v176, v177
	v_pk_add_f32 v[134:135], v[134:135], 1.0 op_sel_hi:[1,0]
	s_nop 0
	v_rcp_f32_e32 v93, v135
	s_nop 0
	v_mul_f32_e32 v135, v91, v93
	v_rcp_f32_e32 v92, v134
	s_nop 0
	v_mul_f32_e32 v134, v90, v92
	v_pk_mul_f32 v[178:179], v[178:179], v[134:135]
	s_nop 0
	v_cvt_pk_bf16_f32 v177, v178, v179
	global_store_dwordx2 v[86:87], v[176:177], off offset:2048
	v_lshl_add_u64 v[86:87], v[86:87], 0, s[18:19]
	s_waitcnt vmcnt(15) lgkmcnt(1)
	v_lshlrev_b32_e32 v92, 16, v136
	v_and_b32_e32 v136, 0xffff0000, v136
	v_mul_f32_e32 v90, 0xbfb8aa3b, v92
	v_mul_f32_e32 v91, 0xbfb8aa3b, v136
	v_exp_f32_e32 v90, v90
	v_exp_f32_e32 v91, v91
	s_nop 0
	v_pk_add_f32 v[90:91], v[90:91], 1.0 op_sel_hi:[1,0]
	s_nop 0
	v_rcp_f32_e32 v94, v91
	s_nop 0
	v_mul_f32_e32 v91, v136, v94
	v_rcp_f32_e32 v93, v90
	s_nop 0
	v_mul_f32_e32 v90, v92, v93
	v_pk_mul_f32 v[180:181], v[180:181], v[90:91]
	v_lshlrev_b32_e32 v90, 16, v137
	v_and_b32_e32 v91, 0xffff0000, v137
	v_mul_f32_e32 v136, 0xbfb8aa3b, v90
	v_mul_f32_e32 v137, 0xbfb8aa3b, v91
	v_exp_f32_e32 v136, v136
	v_exp_f32_e32 v137, v137
	v_cvt_pk_bf16_f32 v180, v180, v181
	v_pk_add_f32 v[136:137], v[136:137], 1.0 op_sel_hi:[1,0]
	s_nop 0
	v_rcp_f32_e32 v93, v137
	s_nop 0
	v_mul_f32_e32 v137, v91, v93
	v_rcp_f32_e32 v92, v136
	s_nop 0
	v_mul_f32_e32 v136, v90, v92
	v_pk_mul_f32 v[182:183], v[182:183], v[136:137]
	s_nop 0
	v_cvt_pk_bf16_f32 v181, v182, v183
	global_store_dwordx2 v[86:87], v[180:181], off offset:2048
	v_lshl_add_u64 v[86:87], v[86:87], 0, s[18:19]
	s_waitcnt vmcnt(15) lgkmcnt(0)
	v_lshlrev_b32_e32 v92, 16, v138
	v_and_b32_e32 v138, 0xffff0000, v138
	v_mul_f32_e32 v90, 0xbfb8aa3b, v92
	v_mul_f32_e32 v91, 0xbfb8aa3b, v138
	v_exp_f32_e32 v90, v90
	v_exp_f32_e32 v91, v91
	s_nop 0
	v_pk_add_f32 v[90:91], v[90:91], 1.0 op_sel_hi:[1,0]
	s_nop 0
	v_rcp_f32_e32 v94, v91
	s_nop 0
	v_mul_f32_e32 v91, v138, v94
	v_rcp_f32_e32 v93, v90
	s_nop 0
	v_mul_f32_e32 v90, v92, v93
	v_pk_mul_f32 v[184:185], v[184:185], v[90:91]
	v_lshlrev_b32_e32 v90, 16, v139
	v_and_b32_e32 v91, 0xffff0000, v139
	v_mul_f32_e32 v138, 0xbfb8aa3b, v90
	v_mul_f32_e32 v139, 0xbfb8aa3b, v91
	v_exp_f32_e32 v138, v138
	v_exp_f32_e32 v139, v139
	v_cvt_pk_bf16_f32 v184, v184, v185
	v_pk_add_f32 v[138:139], v[138:139], 1.0 op_sel_hi:[1,0]
	s_nop 0
	v_rcp_f32_e32 v93, v139
	s_nop 0
	v_mul_f32_e32 v139, v91, v93
	v_rcp_f32_e32 v92, v138
	s_nop 0
	v_mul_f32_e32 v138, v90, v92
	v_pk_mul_f32 v[186:187], v[186:187], v[138:139]
	s_nop 0
	v_cvt_pk_bf16_f32 v185, v186, v187
	global_store_dwordx2 v[86:87], v[184:185], off offset:2048
	v_lshl_add_u64 v[86:87], v[86:87], 0, s[18:19]
	ds_read_b128 v[172:175], v164
	ds_read_b128 v[176:179], v164 offset:8320
	ds_read_b128 v[180:183], v164 offset:16640
	ds_read_b128 v[184:187], v164 offset:24960
	v_add_u32_e32 v164, 0x8200, v164
	s_waitcnt vmcnt(15) lgkmcnt(3)
	v_lshlrev_b32_e32 v92, 16, v140
	v_and_b32_e32 v140, 0xffff0000, v140
	v_mul_f32_e32 v90, 0xbfb8aa3b, v92
	v_mul_f32_e32 v91, 0xbfb8aa3b, v140
	v_exp_f32_e32 v90, v90
	v_exp_f32_e32 v91, v91
	s_nop 0
	v_pk_add_f32 v[90:91], v[90:91], 1.0 op_sel_hi:[1,0]
	s_nop 0
	v_rcp_f32_e32 v94, v91
	s_nop 0
	v_mul_f32_e32 v91, v140, v94
	v_rcp_f32_e32 v93, v90
	s_nop 0
	v_mul_f32_e32 v90, v92, v93
	v_pk_mul_f32 v[172:173], v[172:173], v[90:91]
	v_lshlrev_b32_e32 v90, 16, v141
	v_and_b32_e32 v91, 0xffff0000, v141
	v_mul_f32_e32 v140, 0xbfb8aa3b, v90
	v_mul_f32_e32 v141, 0xbfb8aa3b, v91
	v_exp_f32_e32 v140, v140
	v_exp_f32_e32 v141, v141
	v_cvt_pk_bf16_f32 v172, v172, v173
	v_pk_add_f32 v[140:141], v[140:141], 1.0 op_sel_hi:[1,0]
	s_nop 0
	v_rcp_f32_e32 v93, v141
	s_nop 0
	v_mul_f32_e32 v141, v91, v93
	v_rcp_f32_e32 v92, v140
	s_nop 0
	v_mul_f32_e32 v140, v90, v92
	v_pk_mul_f32 v[174:175], v[174:175], v[140:141]
	s_nop 0
	v_cvt_pk_bf16_f32 v173, v174, v175
	global_store_dwordx2 v[86:87], v[172:173], off offset:2048
	v_lshl_add_u64 v[86:87], v[86:87], 0, s[18:19]
	s_waitcnt vmcnt(15) lgkmcnt(2)
	v_lshlrev_b32_e32 v92, 16, v142
	v_and_b32_e32 v142, 0xffff0000, v142
	v_mul_f32_e32 v90, 0xbfb8aa3b, v92
	v_mul_f32_e32 v91, 0xbfb8aa3b, v142
	v_exp_f32_e32 v90, v90
	v_exp_f32_e32 v91, v91
	s_nop 0
	v_pk_add_f32 v[90:91], v[90:91], 1.0 op_sel_hi:[1,0]
	s_nop 0
	v_rcp_f32_e32 v94, v91
	s_nop 0
	v_mul_f32_e32 v91, v142, v94
	v_rcp_f32_e32 v93, v90
	s_nop 0
	v_mul_f32_e32 v90, v92, v93
	v_pk_mul_f32 v[176:177], v[176:177], v[90:91]
	v_lshlrev_b32_e32 v90, 16, v143
	v_and_b32_e32 v91, 0xffff0000, v143
	v_mul_f32_e32 v142, 0xbfb8aa3b, v90
	v_mul_f32_e32 v143, 0xbfb8aa3b, v91
	v_exp_f32_e32 v142, v142
	v_exp_f32_e32 v143, v143
	v_cvt_pk_bf16_f32 v176, v176, v177
	v_pk_add_f32 v[142:143], v[142:143], 1.0 op_sel_hi:[1,0]
	s_nop 0
	v_rcp_f32_e32 v93, v143
	s_nop 0
	v_mul_f32_e32 v143, v91, v93
	v_rcp_f32_e32 v92, v142
	s_nop 0
	v_mul_f32_e32 v142, v90, v92
	v_pk_mul_f32 v[178:179], v[178:179], v[142:143]
	s_nop 0
	v_cvt_pk_bf16_f32 v177, v178, v179
	global_store_dwordx2 v[86:87], v[176:177], off offset:2048
	v_lshl_add_u64 v[86:87], v[86:87], 0, s[18:19]
	s_waitcnt vmcnt(15) lgkmcnt(1)
	v_lshlrev_b32_e32 v92, 16, v144
	v_and_b32_e32 v144, 0xffff0000, v144
	v_mul_f32_e32 v90, 0xbfb8aa3b, v92
	v_mul_f32_e32 v91, 0xbfb8aa3b, v144
	v_exp_f32_e32 v90, v90
	v_exp_f32_e32 v91, v91
	s_nop 0
	v_pk_add_f32 v[90:91], v[90:91], 1.0 op_sel_hi:[1,0]
	s_nop 0
	v_rcp_f32_e32 v94, v91
	s_nop 0
	v_mul_f32_e32 v91, v144, v94
	v_rcp_f32_e32 v93, v90
	s_nop 0
	v_mul_f32_e32 v90, v92, v93
	v_pk_mul_f32 v[180:181], v[180:181], v[90:91]
	v_lshlrev_b32_e32 v90, 16, v145
	v_and_b32_e32 v91, 0xffff0000, v145
	v_mul_f32_e32 v144, 0xbfb8aa3b, v90
	v_mul_f32_e32 v145, 0xbfb8aa3b, v91
	v_exp_f32_e32 v144, v144
	v_exp_f32_e32 v145, v145
	v_cvt_pk_bf16_f32 v180, v180, v181
	v_pk_add_f32 v[144:145], v[144:145], 1.0 op_sel_hi:[1,0]
	s_nop 0
	v_rcp_f32_e32 v93, v145
	s_nop 0
	v_mul_f32_e32 v145, v91, v93
	v_rcp_f32_e32 v92, v144
	s_nop 0
	v_mul_f32_e32 v144, v90, v92
	v_pk_mul_f32 v[182:183], v[182:183], v[144:145]
	s_nop 0
	v_cvt_pk_bf16_f32 v181, v182, v183
	global_store_dwordx2 v[86:87], v[180:181], off offset:2048
	v_lshl_add_u64 v[86:87], v[86:87], 0, s[18:19]
	s_waitcnt vmcnt(15) lgkmcnt(0)
	v_lshlrev_b32_e32 v92, 16, v146
	v_and_b32_e32 v146, 0xffff0000, v146
	v_mul_f32_e32 v90, 0xbfb8aa3b, v92
	v_mul_f32_e32 v91, 0xbfb8aa3b, v146
	v_exp_f32_e32 v90, v90
	v_exp_f32_e32 v91, v91
	s_nop 0
	v_pk_add_f32 v[90:91], v[90:91], 1.0 op_sel_hi:[1,0]
	s_nop 0
	v_rcp_f32_e32 v94, v91
	s_nop 0
	v_mul_f32_e32 v91, v146, v94
	v_rcp_f32_e32 v93, v90
	s_nop 0
	v_mul_f32_e32 v90, v92, v93
	v_pk_mul_f32 v[184:185], v[184:185], v[90:91]
	v_lshlrev_b32_e32 v90, 16, v147
	v_and_b32_e32 v91, 0xffff0000, v147
	v_mul_f32_e32 v146, 0xbfb8aa3b, v90
	v_mul_f32_e32 v147, 0xbfb8aa3b, v91
	v_exp_f32_e32 v146, v146
	v_exp_f32_e32 v147, v147
	v_cvt_pk_bf16_f32 v184, v184, v185
	v_pk_add_f32 v[146:147], v[146:147], 1.0 op_sel_hi:[1,0]
	s_nop 0
	v_rcp_f32_e32 v93, v147
	s_nop 0
	v_mul_f32_e32 v147, v91, v93
	v_rcp_f32_e32 v92, v146
	s_nop 0
	v_mul_f32_e32 v146, v90, v92
	v_pk_mul_f32 v[186:187], v[186:187], v[146:147]
	s_nop 0
	v_cvt_pk_bf16_f32 v185, v186, v187
	global_store_dwordx2 v[86:87], v[184:185], off offset:2048
	v_lshl_add_u64 v[86:87], v[86:87], 0, s[18:19]
	ds_read_b128 v[172:175], v164
	ds_read_b128 v[176:179], v164 offset:8320
	ds_read_b128 v[180:183], v164 offset:16640
	ds_read_b128 v[184:187], v164 offset:24960
	v_add_u32_e32 v164, 0x8200, v164
	s_waitcnt vmcnt(15) lgkmcnt(3)
	v_lshlrev_b32_e32 v92, 16, v148
	v_and_b32_e32 v148, 0xffff0000, v148
	v_mul_f32_e32 v90, 0xbfb8aa3b, v92
	v_mul_f32_e32 v91, 0xbfb8aa3b, v148
	v_exp_f32_e32 v90, v90
	v_exp_f32_e32 v91, v91
	s_nop 0
	v_pk_add_f32 v[90:91], v[90:91], 1.0 op_sel_hi:[1,0]
	s_nop 0
	v_rcp_f32_e32 v94, v91
	s_nop 0
	v_mul_f32_e32 v91, v148, v94
	v_rcp_f32_e32 v93, v90
	s_nop 0
	v_mul_f32_e32 v90, v92, v93
	v_pk_mul_f32 v[172:173], v[172:173], v[90:91]
	v_lshlrev_b32_e32 v90, 16, v149
	v_and_b32_e32 v91, 0xffff0000, v149
	v_mul_f32_e32 v148, 0xbfb8aa3b, v90
	v_mul_f32_e32 v149, 0xbfb8aa3b, v91
	v_exp_f32_e32 v148, v148
	v_exp_f32_e32 v149, v149
	v_cvt_pk_bf16_f32 v172, v172, v173
	v_pk_add_f32 v[148:149], v[148:149], 1.0 op_sel_hi:[1,0]
	s_nop 0
	v_rcp_f32_e32 v93, v149
	s_nop 0
	v_mul_f32_e32 v149, v91, v93
	v_rcp_f32_e32 v92, v148
	s_nop 0
	v_mul_f32_e32 v148, v90, v92
	v_pk_mul_f32 v[174:175], v[174:175], v[148:149]
	s_nop 0
	v_cvt_pk_bf16_f32 v173, v174, v175
	global_store_dwordx2 v[86:87], v[172:173], off offset:2048
	v_lshl_add_u64 v[86:87], v[86:87], 0, s[18:19]
	s_waitcnt vmcnt(15) lgkmcnt(2)
	v_lshlrev_b32_e32 v92, 16, v150
	v_and_b32_e32 v150, 0xffff0000, v150
	v_mul_f32_e32 v90, 0xbfb8aa3b, v92
	v_mul_f32_e32 v91, 0xbfb8aa3b, v150
	v_exp_f32_e32 v90, v90
	v_exp_f32_e32 v91, v91
	s_nop 0
	v_pk_add_f32 v[90:91], v[90:91], 1.0 op_sel_hi:[1,0]
	s_nop 0
	v_rcp_f32_e32 v94, v91
	s_nop 0
	v_mul_f32_e32 v91, v150, v94
	v_rcp_f32_e32 v93, v90
	s_nop 0
	v_mul_f32_e32 v90, v92, v93
	v_pk_mul_f32 v[176:177], v[176:177], v[90:91]
	v_lshlrev_b32_e32 v90, 16, v151
	v_and_b32_e32 v91, 0xffff0000, v151
	v_mul_f32_e32 v150, 0xbfb8aa3b, v90
	v_mul_f32_e32 v151, 0xbfb8aa3b, v91
	v_exp_f32_e32 v150, v150
	v_exp_f32_e32 v151, v151
	v_cvt_pk_bf16_f32 v176, v176, v177
	v_pk_add_f32 v[150:151], v[150:151], 1.0 op_sel_hi:[1,0]
	s_nop 0
	v_rcp_f32_e32 v93, v151
	s_nop 0
	v_mul_f32_e32 v151, v91, v93
	v_rcp_f32_e32 v92, v150
	s_nop 0
	v_mul_f32_e32 v150, v90, v92
	v_pk_mul_f32 v[178:179], v[178:179], v[150:151]
	s_nop 0
	v_cvt_pk_bf16_f32 v177, v178, v179
	global_store_dwordx2 v[86:87], v[176:177], off offset:2048
	v_lshl_add_u64 v[86:87], v[86:87], 0, s[18:19]
	s_waitcnt vmcnt(15) lgkmcnt(1)
	v_lshlrev_b32_e32 v92, 16, v152
	v_and_b32_e32 v152, 0xffff0000, v152
	v_mul_f32_e32 v90, 0xbfb8aa3b, v92
	v_mul_f32_e32 v91, 0xbfb8aa3b, v152
	v_exp_f32_e32 v90, v90
	v_exp_f32_e32 v91, v91
	s_nop 0
	v_pk_add_f32 v[90:91], v[90:91], 1.0 op_sel_hi:[1,0]
	s_nop 0
	v_rcp_f32_e32 v94, v91
	s_nop 0
	v_mul_f32_e32 v91, v152, v94
	v_rcp_f32_e32 v93, v90
	s_nop 0
	v_mul_f32_e32 v90, v92, v93
	v_pk_mul_f32 v[180:181], v[180:181], v[90:91]
	v_lshlrev_b32_e32 v90, 16, v153
	v_and_b32_e32 v91, 0xffff0000, v153
	v_mul_f32_e32 v152, 0xbfb8aa3b, v90
	v_mul_f32_e32 v153, 0xbfb8aa3b, v91
	v_exp_f32_e32 v152, v152
	v_exp_f32_e32 v153, v153
	v_cvt_pk_bf16_f32 v180, v180, v181
	v_pk_add_f32 v[152:153], v[152:153], 1.0 op_sel_hi:[1,0]
	s_nop 0
	v_rcp_f32_e32 v93, v153
	s_nop 0
	v_mul_f32_e32 v153, v91, v93
	v_rcp_f32_e32 v92, v152
	s_nop 0
	v_mul_f32_e32 v152, v90, v92
	v_pk_mul_f32 v[182:183], v[182:183], v[152:153]
	s_nop 0
	v_cvt_pk_bf16_f32 v181, v182, v183
	global_store_dwordx2 v[86:87], v[180:181], off offset:2048
	v_lshl_add_u64 v[86:87], v[86:87], 0, s[18:19]
	s_waitcnt vmcnt(15) lgkmcnt(0)
	v_lshlrev_b32_e32 v92, 16, v154
	v_and_b32_e32 v154, 0xffff0000, v154
	v_mul_f32_e32 v90, 0xbfb8aa3b, v92
	v_mul_f32_e32 v91, 0xbfb8aa3b, v154
	v_exp_f32_e32 v90, v90
	v_exp_f32_e32 v91, v91
	s_nop 0
	v_pk_add_f32 v[90:91], v[90:91], 1.0 op_sel_hi:[1,0]
	s_nop 0
	v_rcp_f32_e32 v94, v91
	s_nop 0
	v_mul_f32_e32 v91, v154, v94
	v_rcp_f32_e32 v93, v90
	s_nop 0
	v_mul_f32_e32 v90, v92, v93
	v_pk_mul_f32 v[184:185], v[184:185], v[90:91]
	v_lshlrev_b32_e32 v90, 16, v155
	v_and_b32_e32 v91, 0xffff0000, v155
	v_mul_f32_e32 v154, 0xbfb8aa3b, v90
	v_mul_f32_e32 v155, 0xbfb8aa3b, v91
	v_exp_f32_e32 v154, v154
	v_exp_f32_e32 v155, v155
	v_cvt_pk_bf16_f32 v184, v184, v185
	v_pk_add_f32 v[154:155], v[154:155], 1.0 op_sel_hi:[1,0]
	s_nop 0
	v_rcp_f32_e32 v93, v155
	s_nop 0
	v_mul_f32_e32 v155, v91, v93
	v_rcp_f32_e32 v92, v154
	s_nop 0
	v_mul_f32_e32 v154, v90, v92
	v_pk_mul_f32 v[186:187], v[186:187], v[154:155]
	s_nop 0
	v_cvt_pk_bf16_f32 v185, v186, v187
	global_store_dwordx2 v[86:87], v[184:185], off offset:2048
	v_lshl_add_u64 v[86:87], v[86:87], 0, s[18:19]
	ds_read_b128 v[172:175], v164
	ds_read_b128 v[176:179], v164 offset:8320
	ds_read_b128 v[180:183], v164 offset:16640
	ds_read_b128 v[184:187], v164 offset:24960
	v_add_u32_e32 v164, 0x8200, v164
	s_waitcnt vmcnt(15) lgkmcnt(3)
	v_lshlrev_b32_e32 v92, 16, v156
	v_and_b32_e32 v156, 0xffff0000, v156
	v_mul_f32_e32 v90, 0xbfb8aa3b, v92
	v_mul_f32_e32 v91, 0xbfb8aa3b, v156
	v_exp_f32_e32 v90, v90
	v_exp_f32_e32 v91, v91
	s_nop 0
	v_pk_add_f32 v[90:91], v[90:91], 1.0 op_sel_hi:[1,0]
	s_nop 0
	v_rcp_f32_e32 v94, v91
	s_nop 0
	v_mul_f32_e32 v91, v156, v94
	v_rcp_f32_e32 v93, v90
	s_nop 0
	v_mul_f32_e32 v90, v92, v93
	v_pk_mul_f32 v[172:173], v[172:173], v[90:91]
	v_lshlrev_b32_e32 v90, 16, v157
	v_and_b32_e32 v91, 0xffff0000, v157
	v_mul_f32_e32 v156, 0xbfb8aa3b, v90
	v_mul_f32_e32 v157, 0xbfb8aa3b, v91
	v_exp_f32_e32 v156, v156
	v_exp_f32_e32 v157, v157
	v_cvt_pk_bf16_f32 v172, v172, v173
	v_pk_add_f32 v[156:157], v[156:157], 1.0 op_sel_hi:[1,0]
	s_nop 0
	v_rcp_f32_e32 v93, v157
	s_nop 0
	v_mul_f32_e32 v157, v91, v93
	v_rcp_f32_e32 v92, v156
	s_nop 0
	v_mul_f32_e32 v156, v90, v92
	v_pk_mul_f32 v[174:175], v[174:175], v[156:157]
	s_nop 0
	v_cvt_pk_bf16_f32 v173, v174, v175
	global_store_dwordx2 v[86:87], v[172:173], off offset:2048
	v_lshl_add_u64 v[86:87], v[86:87], 0, s[18:19]
	s_waitcnt vmcnt(15) lgkmcnt(2)
	v_lshlrev_b32_e32 v92, 16, v158
	v_and_b32_e32 v158, 0xffff0000, v158
	v_mul_f32_e32 v90, 0xbfb8aa3b, v92
	v_mul_f32_e32 v91, 0xbfb8aa3b, v158
	v_exp_f32_e32 v90, v90
	v_exp_f32_e32 v91, v91
	s_nop 0
	v_pk_add_f32 v[90:91], v[90:91], 1.0 op_sel_hi:[1,0]
	s_nop 0
	v_rcp_f32_e32 v94, v91
	s_nop 0
	v_mul_f32_e32 v91, v158, v94
	v_rcp_f32_e32 v93, v90
	s_nop 0
	v_mul_f32_e32 v90, v92, v93
	v_pk_mul_f32 v[176:177], v[176:177], v[90:91]
	v_lshlrev_b32_e32 v90, 16, v159
	v_and_b32_e32 v91, 0xffff0000, v159
	v_mul_f32_e32 v158, 0xbfb8aa3b, v90
	v_mul_f32_e32 v159, 0xbfb8aa3b, v91
	v_exp_f32_e32 v158, v158
	v_exp_f32_e32 v159, v159
	v_cvt_pk_bf16_f32 v176, v176, v177
	v_pk_add_f32 v[158:159], v[158:159], 1.0 op_sel_hi:[1,0]
	s_nop 0
	v_rcp_f32_e32 v93, v159
	s_nop 0
	v_mul_f32_e32 v159, v91, v93
	v_rcp_f32_e32 v92, v158
	s_nop 0
	v_mul_f32_e32 v158, v90, v92
	v_pk_mul_f32 v[178:179], v[178:179], v[158:159]
	s_nop 0
	v_cvt_pk_bf16_f32 v177, v178, v179
	global_store_dwordx2 v[86:87], v[176:177], off offset:2048
	v_lshl_add_u64 v[86:87], v[86:87], 0, s[18:19]
	s_waitcnt vmcnt(15) lgkmcnt(1)
	v_lshlrev_b32_e32 v92, 16, v160
	v_and_b32_e32 v160, 0xffff0000, v160
	v_mul_f32_e32 v90, 0xbfb8aa3b, v92
	v_mul_f32_e32 v91, 0xbfb8aa3b, v160
	v_exp_f32_e32 v90, v90
	v_exp_f32_e32 v91, v91
	s_nop 0
	v_pk_add_f32 v[90:91], v[90:91], 1.0 op_sel_hi:[1,0]
	s_nop 0
	v_rcp_f32_e32 v94, v91
	s_nop 0
	v_mul_f32_e32 v91, v160, v94
	v_rcp_f32_e32 v93, v90
	s_nop 0
	v_mul_f32_e32 v90, v92, v93
	v_pk_mul_f32 v[180:181], v[180:181], v[90:91]
	v_lshlrev_b32_e32 v90, 16, v161
	v_and_b32_e32 v91, 0xffff0000, v161
	v_mul_f32_e32 v160, 0xbfb8aa3b, v90
	v_mul_f32_e32 v161, 0xbfb8aa3b, v91
	v_exp_f32_e32 v160, v160
	v_exp_f32_e32 v161, v161
	v_cvt_pk_bf16_f32 v180, v180, v181
	v_pk_add_f32 v[160:161], v[160:161], 1.0 op_sel_hi:[1,0]
	s_nop 0
	v_rcp_f32_e32 v93, v161
	s_nop 0
	v_mul_f32_e32 v161, v91, v93
	v_rcp_f32_e32 v92, v160
	s_nop 0
	v_mul_f32_e32 v160, v90, v92
	v_pk_mul_f32 v[182:183], v[182:183], v[160:161]
	s_nop 0
	v_cvt_pk_bf16_f32 v181, v182, v183
	global_store_dwordx2 v[86:87], v[180:181], off offset:2048
	v_lshl_add_u64 v[86:87], v[86:87], 0, s[18:19]
	s_waitcnt vmcnt(15) lgkmcnt(0)
	v_lshlrev_b32_e32 v92, 16, v162
	v_and_b32_e32 v162, 0xffff0000, v162
	v_mul_f32_e32 v90, 0xbfb8aa3b, v92
	v_mul_f32_e32 v91, 0xbfb8aa3b, v162
	v_exp_f32_e32 v90, v90
	v_exp_f32_e32 v91, v91
	s_nop 0
	v_pk_add_f32 v[90:91], v[90:91], 1.0 op_sel_hi:[1,0]
	s_nop 0
	v_rcp_f32_e32 v94, v91
	s_nop 0
	v_mul_f32_e32 v91, v162, v94
	v_rcp_f32_e32 v93, v90
	s_nop 0
	v_mul_f32_e32 v90, v92, v93
	v_pk_mul_f32 v[184:185], v[184:185], v[90:91]
	v_lshlrev_b32_e32 v90, 16, v163
	v_and_b32_e32 v91, 0xffff0000, v163
	v_mul_f32_e32 v162, 0xbfb8aa3b, v90
	v_mul_f32_e32 v163, 0xbfb8aa3b, v91
	v_exp_f32_e32 v162, v162
	v_exp_f32_e32 v163, v163
	v_cvt_pk_bf16_f32 v184, v184, v185
	v_pk_add_f32 v[162:163], v[162:163], 1.0 op_sel_hi:[1,0]
	s_nop 0
	v_rcp_f32_e32 v93, v163
	s_nop 0
	v_mul_f32_e32 v163, v91, v93
	v_rcp_f32_e32 v92, v162
	s_nop 0
	v_mul_f32_e32 v162, v90, v92
	v_pk_mul_f32 v[186:187], v[186:187], v[162:163]
	s_nop 0
	v_cvt_pk_bf16_f32 v185, v186, v187
	global_store_dwordx2 v[86:87], v[184:185], off offset:2048
	v_lshl_add_u64 v[86:87], v[86:87], 0, s[18:19]
	s_addk_i32 s0, 0x80
	s_mov_b32 s17, 0
	s_barrier
	ds_write2_b32 v131, v2, v18 offset1:16
	ds_write2_b32 v114, v3, v19 offset0:4 offset1:20
	ds_write2_b32 v115, v4, v20 offset0:8 offset1:24
	ds_write2_b32 v116, v5, v21 offset0:12 offset1:28
	ds_write2_b32 v117, v6, v22 offset0:64 offset1:80
	ds_write2_b32 v82, v7, v23 offset0:68 offset1:84
	ds_write2_b32 v83, v8, v24 offset0:72 offset1:88
	ds_write2_b32 v84, v9, v25 offset0:76 offset1:92
	ds_write2_b32 v85, v10, v26 offset0:128 offset1:144
	ds_write2_b32 v74, v11, v27 offset0:132 offset1:148
	ds_write2_b32 v75, v12, v28 offset0:136 offset1:152
	ds_write2_b32 v76, v13, v29 offset0:140 offset1:156
	ds_write2_b32 v77, v14, v30 offset0:192 offset1:208
	ds_write2_b32 v70, v15, v31 offset0:196 offset1:212
	ds_write2_b32 v71, v16, v32 offset0:200 offset1:216
	ds_write2_b32 v68, v17, v33 offset0:204 offset1:220
	ds_write2_b32 v131, v34, v50 offset0:128 offset1:144
	ds_write2_b32 v114, v35, v51 offset0:132 offset1:148
	ds_write2_b32 v115, v36, v52 offset0:136 offset1:152
	ds_write2_b32 v116, v37, v53 offset0:140 offset1:156
	ds_write2_b32 v117, v38, v54 offset0:192 offset1:208
	ds_write2_b32 v82, v39, v55 offset0:196 offset1:212
	ds_write2_b32 v83, v40, v56 offset0:200 offset1:216
	ds_write2_b32 v84, v41, v57 offset0:204 offset1:220
	ds_write2_b32 v74, v42, v58 offset1:16
	ds_write2_b32 v75, v43, v59 offset0:4 offset1:20
	ds_write2_b32 v76, v44, v60 offset0:8 offset1:24
	ds_write2_b32 v69, v45, v61 offset0:12 offset1:28
	ds_write2_b32 v70, v46, v62 offset0:64 offset1:80
	ds_write2_b32 v71, v47, v63 offset0:68 offset1:84
	ds_write2_b32 v68, v48, v64 offset0:72 offset1:88
	ds_write2_b32 v72, v49, v65 offset0:76 offset1:92
	s_waitcnt lgkmcnt(0)
	s_barrier
.LBB0_211:
	v_ashrrev_i32_e32 v165, 6, v130
	v_mad_u32_u24 v164, v165, s33, v0
	v_add_u32_e32 v165, s0, v165
	v_mad_i64_i32 v[86:87], s[18:19], v165, s96, v[66:67]
	s_mov_b32 s18, 0x1c000
	s_mov_b32 s19, 0
	global_load_dwordx2 v[132:133], v[86:87], off offset:1024
	v_lshl_add_u64 v[86:87], v[86:87], 0, s[18:19]
	global_load_dwordx2 v[134:135], v[86:87], off offset:1024
	v_lshl_add_u64 v[86:87], v[86:87], 0, s[18:19]
	global_load_dwordx2 v[136:137], v[86:87], off offset:1024
	v_lshl_add_u64 v[86:87], v[86:87], 0, s[18:19]
	global_load_dwordx2 v[138:139], v[86:87], off offset:1024
	v_lshl_add_u64 v[86:87], v[86:87], 0, s[18:19]
	global_load_dwordx2 v[140:141], v[86:87], off offset:1024
	v_lshl_add_u64 v[86:87], v[86:87], 0, s[18:19]
	global_load_dwordx2 v[142:143], v[86:87], off offset:1024
	v_lshl_add_u64 v[86:87], v[86:87], 0, s[18:19]
	global_load_dwordx2 v[144:145], v[86:87], off offset:1024
	v_lshl_add_u64 v[86:87], v[86:87], 0, s[18:19]
	global_load_dwordx2 v[146:147], v[86:87], off offset:1024
	v_lshl_add_u64 v[86:87], v[86:87], 0, s[18:19]
	global_load_dwordx2 v[148:149], v[86:87], off offset:1024
	v_lshl_add_u64 v[86:87], v[86:87], 0, s[18:19]
	global_load_dwordx2 v[150:151], v[86:87], off offset:1024
	v_lshl_add_u64 v[86:87], v[86:87], 0, s[18:19]
	global_load_dwordx2 v[152:153], v[86:87], off offset:1024
	v_lshl_add_u64 v[86:87], v[86:87], 0, s[18:19]
	global_load_dwordx2 v[154:155], v[86:87], off offset:1024
	v_lshl_add_u64 v[86:87], v[86:87], 0, s[18:19]
	global_load_dwordx2 v[156:157], v[86:87], off offset:1024
	v_lshl_add_u64 v[86:87], v[86:87], 0, s[18:19]
	global_load_dwordx2 v[158:159], v[86:87], off offset:1024
	v_lshl_add_u64 v[86:87], v[86:87], 0, s[18:19]
	global_load_dwordx2 v[160:161], v[86:87], off offset:1024
	v_lshl_add_u64 v[86:87], v[86:87], 0, s[18:19]
	global_load_dwordx2 v[162:163], v[86:87], off offset:1024
	v_lshl_add_u64 v[86:87], v[86:87], 0, s[18:19]
	s_mov_b32 s18, 0xffe40000
	s_mov_b32 s19, -1
	v_lshl_add_u64 v[86:87], v[86:87], 0, s[18:19]
	s_mov_b32 s18, 0x1c000
	s_mov_b32 s19, 0
	ds_read_b128 v[172:175], v164
	ds_read_b128 v[176:179], v164 offset:8320
	ds_read_b128 v[180:183], v164 offset:16640
	ds_read_b128 v[184:187], v164 offset:24960
	v_add_u32_e32 v164, 0x8200, v164
	s_waitcnt vmcnt(15) lgkmcnt(3)
	v_lshlrev_b32_e32 v92, 16, v132
	v_and_b32_e32 v132, 0xffff0000, v132
	v_mul_f32_e32 v90, 0xbfb8aa3b, v92
	v_mul_f32_e32 v91, 0xbfb8aa3b, v132
	v_exp_f32_e32 v90, v90
	v_exp_f32_e32 v91, v91
	s_nop 0
	v_pk_add_f32 v[90:91], v[90:91], 1.0 op_sel_hi:[1,0]
	s_nop 0
	v_rcp_f32_e32 v94, v91
	s_nop 0
	v_mul_f32_e32 v91, v132, v94
	v_rcp_f32_e32 v93, v90
	s_nop 0
	v_mul_f32_e32 v90, v92, v93
	v_pk_mul_f32 v[172:173], v[172:173], v[90:91]
	v_lshlrev_b32_e32 v90, 16, v133
	v_and_b32_e32 v91, 0xffff0000, v133
	v_mul_f32_e32 v132, 0xbfb8aa3b, v90
	v_mul_f32_e32 v133, 0xbfb8aa3b, v91
	v_exp_f32_e32 v132, v132
	v_exp_f32_e32 v133, v133
	v_cvt_pk_bf16_f32 v172, v172, v173
	v_pk_add_f32 v[132:133], v[132:133], 1.0 op_sel_hi:[1,0]
	s_nop 0
	v_rcp_f32_e32 v93, v133
	s_nop 0
	v_mul_f32_e32 v133, v91, v93
	v_rcp_f32_e32 v92, v132
	s_nop 0
	v_mul_f32_e32 v132, v90, v92
	v_pk_mul_f32 v[174:175], v[174:175], v[132:133]
	s_nop 0
	v_cvt_pk_bf16_f32 v173, v174, v175
	global_store_dwordx2 v[86:87], v[172:173], off offset:2048
	v_lshl_add_u64 v[86:87], v[86:87], 0, s[18:19]
	s_waitcnt vmcnt(15) lgkmcnt(2)
	v_lshlrev_b32_e32 v92, 16, v134
	v_and_b32_e32 v134, 0xffff0000, v134
	v_mul_f32_e32 v90, 0xbfb8aa3b, v92
	v_mul_f32_e32 v91, 0xbfb8aa3b, v134
	v_exp_f32_e32 v90, v90
	v_exp_f32_e32 v91, v91
	s_nop 0
	v_pk_add_f32 v[90:91], v[90:91], 1.0 op_sel_hi:[1,0]
	s_nop 0
	v_rcp_f32_e32 v94, v91
	s_nop 0
	v_mul_f32_e32 v91, v134, v94
	v_rcp_f32_e32 v93, v90
	s_nop 0
	v_mul_f32_e32 v90, v92, v93
	v_pk_mul_f32 v[176:177], v[176:177], v[90:91]
	v_lshlrev_b32_e32 v90, 16, v135
	v_and_b32_e32 v91, 0xffff0000, v135
	v_mul_f32_e32 v134, 0xbfb8aa3b, v90
	v_mul_f32_e32 v135, 0xbfb8aa3b, v91
	v_exp_f32_e32 v134, v134
	v_exp_f32_e32 v135, v135
	v_cvt_pk_bf16_f32 v176, v176, v177
	v_pk_add_f32 v[134:135], v[134:135], 1.0 op_sel_hi:[1,0]
	s_nop 0
	v_rcp_f32_e32 v93, v135
	s_nop 0
	v_mul_f32_e32 v135, v91, v93
	v_rcp_f32_e32 v92, v134
	s_nop 0
	v_mul_f32_e32 v134, v90, v92
	v_pk_mul_f32 v[178:179], v[178:179], v[134:135]
	s_nop 0
	v_cvt_pk_bf16_f32 v177, v178, v179
	global_store_dwordx2 v[86:87], v[176:177], off offset:2048
	v_lshl_add_u64 v[86:87], v[86:87], 0, s[18:19]
	s_waitcnt vmcnt(15) lgkmcnt(1)
	v_lshlrev_b32_e32 v92, 16, v136
	v_and_b32_e32 v136, 0xffff0000, v136
	v_mul_f32_e32 v90, 0xbfb8aa3b, v92
	v_mul_f32_e32 v91, 0xbfb8aa3b, v136
	v_exp_f32_e32 v90, v90
	v_exp_f32_e32 v91, v91
	s_nop 0
	v_pk_add_f32 v[90:91], v[90:91], 1.0 op_sel_hi:[1,0]
	s_nop 0
	v_rcp_f32_e32 v94, v91
	s_nop 0
	v_mul_f32_e32 v91, v136, v94
	v_rcp_f32_e32 v93, v90
	s_nop 0
	v_mul_f32_e32 v90, v92, v93
	v_pk_mul_f32 v[180:181], v[180:181], v[90:91]
	v_lshlrev_b32_e32 v90, 16, v137
	v_and_b32_e32 v91, 0xffff0000, v137
	v_mul_f32_e32 v136, 0xbfb8aa3b, v90
	v_mul_f32_e32 v137, 0xbfb8aa3b, v91
	v_exp_f32_e32 v136, v136
	v_exp_f32_e32 v137, v137
	v_cvt_pk_bf16_f32 v180, v180, v181
	v_pk_add_f32 v[136:137], v[136:137], 1.0 op_sel_hi:[1,0]
	s_nop 0
	v_rcp_f32_e32 v93, v137
	s_nop 0
	v_mul_f32_e32 v137, v91, v93
	v_rcp_f32_e32 v92, v136
	s_nop 0
	v_mul_f32_e32 v136, v90, v92
	v_pk_mul_f32 v[182:183], v[182:183], v[136:137]
	s_nop 0
	v_cvt_pk_bf16_f32 v181, v182, v183
	global_store_dwordx2 v[86:87], v[180:181], off offset:2048
	v_lshl_add_u64 v[86:87], v[86:87], 0, s[18:19]
	s_waitcnt vmcnt(15) lgkmcnt(0)
	v_lshlrev_b32_e32 v92, 16, v138
	v_and_b32_e32 v138, 0xffff0000, v138
	v_mul_f32_e32 v90, 0xbfb8aa3b, v92
	v_mul_f32_e32 v91, 0xbfb8aa3b, v138
	v_exp_f32_e32 v90, v90
	v_exp_f32_e32 v91, v91
	s_nop 0
	v_pk_add_f32 v[90:91], v[90:91], 1.0 op_sel_hi:[1,0]
	s_nop 0
	v_rcp_f32_e32 v94, v91
	s_nop 0
	v_mul_f32_e32 v91, v138, v94
	v_rcp_f32_e32 v93, v90
	s_nop 0
	v_mul_f32_e32 v90, v92, v93
	v_pk_mul_f32 v[184:185], v[184:185], v[90:91]
	v_lshlrev_b32_e32 v90, 16, v139
	v_and_b32_e32 v91, 0xffff0000, v139
	v_mul_f32_e32 v138, 0xbfb8aa3b, v90
	v_mul_f32_e32 v139, 0xbfb8aa3b, v91
	v_exp_f32_e32 v138, v138
	v_exp_f32_e32 v139, v139
	v_cvt_pk_bf16_f32 v184, v184, v185
	v_pk_add_f32 v[138:139], v[138:139], 1.0 op_sel_hi:[1,0]
	s_nop 0
	v_rcp_f32_e32 v93, v139
	s_nop 0
	v_mul_f32_e32 v139, v91, v93
	v_rcp_f32_e32 v92, v138
	s_nop 0
	v_mul_f32_e32 v138, v90, v92
	v_pk_mul_f32 v[186:187], v[186:187], v[138:139]
	s_nop 0
	v_cvt_pk_bf16_f32 v185, v186, v187
	global_store_dwordx2 v[86:87], v[184:185], off offset:2048
	v_lshl_add_u64 v[86:87], v[86:87], 0, s[18:19]
	ds_read_b128 v[172:175], v164
	ds_read_b128 v[176:179], v164 offset:8320
	ds_read_b128 v[180:183], v164 offset:16640
	ds_read_b128 v[184:187], v164 offset:24960
	v_add_u32_e32 v164, 0x8200, v164
	s_waitcnt vmcnt(15) lgkmcnt(3)
	v_lshlrev_b32_e32 v92, 16, v140
	v_and_b32_e32 v140, 0xffff0000, v140
	v_mul_f32_e32 v90, 0xbfb8aa3b, v92
	v_mul_f32_e32 v91, 0xbfb8aa3b, v140
	v_exp_f32_e32 v90, v90
	v_exp_f32_e32 v91, v91
	s_nop 0
	v_pk_add_f32 v[90:91], v[90:91], 1.0 op_sel_hi:[1,0]
	s_nop 0
	v_rcp_f32_e32 v94, v91
	s_nop 0
	v_mul_f32_e32 v91, v140, v94
	v_rcp_f32_e32 v93, v90
	s_nop 0
	v_mul_f32_e32 v90, v92, v93
	v_pk_mul_f32 v[172:173], v[172:173], v[90:91]
	v_lshlrev_b32_e32 v90, 16, v141
	v_and_b32_e32 v91, 0xffff0000, v141
	v_mul_f32_e32 v140, 0xbfb8aa3b, v90
	v_mul_f32_e32 v141, 0xbfb8aa3b, v91
	v_exp_f32_e32 v140, v140
	v_exp_f32_e32 v141, v141
	v_cvt_pk_bf16_f32 v172, v172, v173
	v_pk_add_f32 v[140:141], v[140:141], 1.0 op_sel_hi:[1,0]
	s_nop 0
	v_rcp_f32_e32 v93, v141
	s_nop 0
	v_mul_f32_e32 v141, v91, v93
	v_rcp_f32_e32 v92, v140
	s_nop 0
	v_mul_f32_e32 v140, v90, v92
	v_pk_mul_f32 v[174:175], v[174:175], v[140:141]
	s_nop 0
	v_cvt_pk_bf16_f32 v173, v174, v175
	global_store_dwordx2 v[86:87], v[172:173], off offset:2048
	v_lshl_add_u64 v[86:87], v[86:87], 0, s[18:19]
	s_waitcnt vmcnt(15) lgkmcnt(2)
	v_lshlrev_b32_e32 v92, 16, v142
	v_and_b32_e32 v142, 0xffff0000, v142
	v_mul_f32_e32 v90, 0xbfb8aa3b, v92
	v_mul_f32_e32 v91, 0xbfb8aa3b, v142
	v_exp_f32_e32 v90, v90
	v_exp_f32_e32 v91, v91
	s_nop 0
	v_pk_add_f32 v[90:91], v[90:91], 1.0 op_sel_hi:[1,0]
	s_nop 0
	v_rcp_f32_e32 v94, v91
	s_nop 0
	v_mul_f32_e32 v91, v142, v94
	v_rcp_f32_e32 v93, v90
	s_nop 0
	v_mul_f32_e32 v90, v92, v93
	v_pk_mul_f32 v[176:177], v[176:177], v[90:91]
	v_lshlrev_b32_e32 v90, 16, v143
	v_and_b32_e32 v91, 0xffff0000, v143
	v_mul_f32_e32 v142, 0xbfb8aa3b, v90
	v_mul_f32_e32 v143, 0xbfb8aa3b, v91
	v_exp_f32_e32 v142, v142
	v_exp_f32_e32 v143, v143
	v_cvt_pk_bf16_f32 v176, v176, v177
	v_pk_add_f32 v[142:143], v[142:143], 1.0 op_sel_hi:[1,0]
	s_nop 0
	v_rcp_f32_e32 v93, v143
	s_nop 0
	v_mul_f32_e32 v143, v91, v93
	v_rcp_f32_e32 v92, v142
	s_nop 0
	v_mul_f32_e32 v142, v90, v92
	v_pk_mul_f32 v[178:179], v[178:179], v[142:143]
	s_nop 0
	v_cvt_pk_bf16_f32 v177, v178, v179
	global_store_dwordx2 v[86:87], v[176:177], off offset:2048
	v_lshl_add_u64 v[86:87], v[86:87], 0, s[18:19]
	s_waitcnt vmcnt(15) lgkmcnt(1)
	v_lshlrev_b32_e32 v92, 16, v144
	v_and_b32_e32 v144, 0xffff0000, v144
	v_mul_f32_e32 v90, 0xbfb8aa3b, v92
	v_mul_f32_e32 v91, 0xbfb8aa3b, v144
	v_exp_f32_e32 v90, v90
	v_exp_f32_e32 v91, v91
	s_nop 0
	v_pk_add_f32 v[90:91], v[90:91], 1.0 op_sel_hi:[1,0]
	s_nop 0
	v_rcp_f32_e32 v94, v91
	s_nop 0
	v_mul_f32_e32 v91, v144, v94
	v_rcp_f32_e32 v93, v90
	s_nop 0
	v_mul_f32_e32 v90, v92, v93
	v_pk_mul_f32 v[180:181], v[180:181], v[90:91]
	v_lshlrev_b32_e32 v90, 16, v145
	v_and_b32_e32 v91, 0xffff0000, v145
	v_mul_f32_e32 v144, 0xbfb8aa3b, v90
	v_mul_f32_e32 v145, 0xbfb8aa3b, v91
	v_exp_f32_e32 v144, v144
	v_exp_f32_e32 v145, v145
	v_cvt_pk_bf16_f32 v180, v180, v181
	v_pk_add_f32 v[144:145], v[144:145], 1.0 op_sel_hi:[1,0]
	s_nop 0
	v_rcp_f32_e32 v93, v145
	s_nop 0
	v_mul_f32_e32 v145, v91, v93
	v_rcp_f32_e32 v92, v144
	s_nop 0
	v_mul_f32_e32 v144, v90, v92
	v_pk_mul_f32 v[182:183], v[182:183], v[144:145]
	s_nop 0
	v_cvt_pk_bf16_f32 v181, v182, v183
	global_store_dwordx2 v[86:87], v[180:181], off offset:2048
	v_lshl_add_u64 v[86:87], v[86:87], 0, s[18:19]
	s_waitcnt vmcnt(15) lgkmcnt(0)
	v_lshlrev_b32_e32 v92, 16, v146
	v_and_b32_e32 v146, 0xffff0000, v146
	v_mul_f32_e32 v90, 0xbfb8aa3b, v92
	v_mul_f32_e32 v91, 0xbfb8aa3b, v146
	v_exp_f32_e32 v90, v90
	v_exp_f32_e32 v91, v91
	s_nop 0
	v_pk_add_f32 v[90:91], v[90:91], 1.0 op_sel_hi:[1,0]
	s_nop 0
	v_rcp_f32_e32 v94, v91
	s_nop 0
	v_mul_f32_e32 v91, v146, v94
	v_rcp_f32_e32 v93, v90
	s_nop 0
	v_mul_f32_e32 v90, v92, v93
	v_pk_mul_f32 v[184:185], v[184:185], v[90:91]
	v_lshlrev_b32_e32 v90, 16, v147
	v_and_b32_e32 v91, 0xffff0000, v147
	v_mul_f32_e32 v146, 0xbfb8aa3b, v90
	v_mul_f32_e32 v147, 0xbfb8aa3b, v91
	v_exp_f32_e32 v146, v146
	v_exp_f32_e32 v147, v147
	v_cvt_pk_bf16_f32 v184, v184, v185
	v_pk_add_f32 v[146:147], v[146:147], 1.0 op_sel_hi:[1,0]
	s_nop 0
	v_rcp_f32_e32 v93, v147
	s_nop 0
	v_mul_f32_e32 v147, v91, v93
	v_rcp_f32_e32 v92, v146
	s_nop 0
	v_mul_f32_e32 v146, v90, v92
	v_pk_mul_f32 v[186:187], v[186:187], v[146:147]
	s_nop 0
	v_cvt_pk_bf16_f32 v185, v186, v187
	global_store_dwordx2 v[86:87], v[184:185], off offset:2048
	v_lshl_add_u64 v[86:87], v[86:87], 0, s[18:19]
	ds_read_b128 v[172:175], v164
	ds_read_b128 v[176:179], v164 offset:8320
	ds_read_b128 v[180:183], v164 offset:16640
	ds_read_b128 v[184:187], v164 offset:24960
	v_add_u32_e32 v164, 0x8200, v164
	s_waitcnt vmcnt(15) lgkmcnt(3)
	v_lshlrev_b32_e32 v92, 16, v148
	v_and_b32_e32 v148, 0xffff0000, v148
	v_mul_f32_e32 v90, 0xbfb8aa3b, v92
	v_mul_f32_e32 v91, 0xbfb8aa3b, v148
	v_exp_f32_e32 v90, v90
	v_exp_f32_e32 v91, v91
	s_nop 0
	v_pk_add_f32 v[90:91], v[90:91], 1.0 op_sel_hi:[1,0]
	s_nop 0
	v_rcp_f32_e32 v94, v91
	s_nop 0
	v_mul_f32_e32 v91, v148, v94
	v_rcp_f32_e32 v93, v90
	s_nop 0
	v_mul_f32_e32 v90, v92, v93
	v_pk_mul_f32 v[172:173], v[172:173], v[90:91]
	v_lshlrev_b32_e32 v90, 16, v149
	v_and_b32_e32 v91, 0xffff0000, v149
	v_mul_f32_e32 v148, 0xbfb8aa3b, v90
	v_mul_f32_e32 v149, 0xbfb8aa3b, v91
	v_exp_f32_e32 v148, v148
	v_exp_f32_e32 v149, v149
	v_cvt_pk_bf16_f32 v172, v172, v173
	v_pk_add_f32 v[148:149], v[148:149], 1.0 op_sel_hi:[1,0]
	s_nop 0
	v_rcp_f32_e32 v93, v149
	s_nop 0
	v_mul_f32_e32 v149, v91, v93
	v_rcp_f32_e32 v92, v148
	s_nop 0
	v_mul_f32_e32 v148, v90, v92
	v_pk_mul_f32 v[174:175], v[174:175], v[148:149]
	s_nop 0
	v_cvt_pk_bf16_f32 v173, v174, v175
	global_store_dwordx2 v[86:87], v[172:173], off offset:2048
	v_lshl_add_u64 v[86:87], v[86:87], 0, s[18:19]
	s_waitcnt vmcnt(15) lgkmcnt(2)
	v_lshlrev_b32_e32 v92, 16, v150
	v_and_b32_e32 v150, 0xffff0000, v150
	v_mul_f32_e32 v90, 0xbfb8aa3b, v92
	v_mul_f32_e32 v91, 0xbfb8aa3b, v150
	v_exp_f32_e32 v90, v90
	v_exp_f32_e32 v91, v91
	s_nop 0
	v_pk_add_f32 v[90:91], v[90:91], 1.0 op_sel_hi:[1,0]
	s_nop 0
	v_rcp_f32_e32 v94, v91
	s_nop 0
	v_mul_f32_e32 v91, v150, v94
	v_rcp_f32_e32 v93, v90
	s_nop 0
	v_mul_f32_e32 v90, v92, v93
	v_pk_mul_f32 v[176:177], v[176:177], v[90:91]
	v_lshlrev_b32_e32 v90, 16, v151
	v_and_b32_e32 v91, 0xffff0000, v151
	v_mul_f32_e32 v150, 0xbfb8aa3b, v90
	v_mul_f32_e32 v151, 0xbfb8aa3b, v91
	v_exp_f32_e32 v150, v150
	v_exp_f32_e32 v151, v151
	v_cvt_pk_bf16_f32 v176, v176, v177
	v_pk_add_f32 v[150:151], v[150:151], 1.0 op_sel_hi:[1,0]
	s_nop 0
	v_rcp_f32_e32 v93, v151
	s_nop 0
	v_mul_f32_e32 v151, v91, v93
	v_rcp_f32_e32 v92, v150
	s_nop 0
	v_mul_f32_e32 v150, v90, v92
	v_pk_mul_f32 v[178:179], v[178:179], v[150:151]
	s_nop 0
	v_cvt_pk_bf16_f32 v177, v178, v179
	global_store_dwordx2 v[86:87], v[176:177], off offset:2048
	v_lshl_add_u64 v[86:87], v[86:87], 0, s[18:19]
	s_waitcnt vmcnt(15) lgkmcnt(1)
	v_lshlrev_b32_e32 v92, 16, v152
	v_and_b32_e32 v152, 0xffff0000, v152
	v_mul_f32_e32 v90, 0xbfb8aa3b, v92
	v_mul_f32_e32 v91, 0xbfb8aa3b, v152
	v_exp_f32_e32 v90, v90
	v_exp_f32_e32 v91, v91
	s_nop 0
	v_pk_add_f32 v[90:91], v[90:91], 1.0 op_sel_hi:[1,0]
	s_nop 0
	v_rcp_f32_e32 v94, v91
	s_nop 0
	v_mul_f32_e32 v91, v152, v94
	v_rcp_f32_e32 v93, v90
	s_nop 0
	v_mul_f32_e32 v90, v92, v93
	v_pk_mul_f32 v[180:181], v[180:181], v[90:91]
	v_lshlrev_b32_e32 v90, 16, v153
	v_and_b32_e32 v91, 0xffff0000, v153
	v_mul_f32_e32 v152, 0xbfb8aa3b, v90
	v_mul_f32_e32 v153, 0xbfb8aa3b, v91
	v_exp_f32_e32 v152, v152
	v_exp_f32_e32 v153, v153
	v_cvt_pk_bf16_f32 v180, v180, v181
	v_pk_add_f32 v[152:153], v[152:153], 1.0 op_sel_hi:[1,0]
	s_nop 0
	v_rcp_f32_e32 v93, v153
	s_nop 0
	v_mul_f32_e32 v153, v91, v93
	v_rcp_f32_e32 v92, v152
	s_nop 0
	v_mul_f32_e32 v152, v90, v92
	v_pk_mul_f32 v[182:183], v[182:183], v[152:153]
	s_nop 0
	v_cvt_pk_bf16_f32 v181, v182, v183
	global_store_dwordx2 v[86:87], v[180:181], off offset:2048
	v_lshl_add_u64 v[86:87], v[86:87], 0, s[18:19]
	s_waitcnt vmcnt(15) lgkmcnt(0)
	v_lshlrev_b32_e32 v92, 16, v154
	v_and_b32_e32 v154, 0xffff0000, v154
	v_mul_f32_e32 v90, 0xbfb8aa3b, v92
	v_mul_f32_e32 v91, 0xbfb8aa3b, v154
	v_exp_f32_e32 v90, v90
	v_exp_f32_e32 v91, v91
	s_nop 0
	v_pk_add_f32 v[90:91], v[90:91], 1.0 op_sel_hi:[1,0]
	s_nop 0
	v_rcp_f32_e32 v94, v91
	s_nop 0
	v_mul_f32_e32 v91, v154, v94
	v_rcp_f32_e32 v93, v90
	s_nop 0
	v_mul_f32_e32 v90, v92, v93
	v_pk_mul_f32 v[184:185], v[184:185], v[90:91]
	v_lshlrev_b32_e32 v90, 16, v155
	v_and_b32_e32 v91, 0xffff0000, v155
	v_mul_f32_e32 v154, 0xbfb8aa3b, v90
	v_mul_f32_e32 v155, 0xbfb8aa3b, v91
	v_exp_f32_e32 v154, v154
	v_exp_f32_e32 v155, v155
	v_cvt_pk_bf16_f32 v184, v184, v185
	v_pk_add_f32 v[154:155], v[154:155], 1.0 op_sel_hi:[1,0]
	s_nop 0
	v_rcp_f32_e32 v93, v155
	s_nop 0
	v_mul_f32_e32 v155, v91, v93
	v_rcp_f32_e32 v92, v154
	s_nop 0
	v_mul_f32_e32 v154, v90, v92
	v_pk_mul_f32 v[186:187], v[186:187], v[154:155]
	s_nop 0
	v_cvt_pk_bf16_f32 v185, v186, v187
	global_store_dwordx2 v[86:87], v[184:185], off offset:2048
	v_lshl_add_u64 v[86:87], v[86:87], 0, s[18:19]
	ds_read_b128 v[172:175], v164
	ds_read_b128 v[176:179], v164 offset:8320
	ds_read_b128 v[180:183], v164 offset:16640
	ds_read_b128 v[184:187], v164 offset:24960
	v_add_u32_e32 v164, 0x8200, v164
	s_waitcnt vmcnt(15) lgkmcnt(3)
	v_lshlrev_b32_e32 v92, 16, v156
	v_and_b32_e32 v156, 0xffff0000, v156
	v_mul_f32_e32 v90, 0xbfb8aa3b, v92
	v_mul_f32_e32 v91, 0xbfb8aa3b, v156
	v_exp_f32_e32 v90, v90
	v_exp_f32_e32 v91, v91
	s_nop 0
	v_pk_add_f32 v[90:91], v[90:91], 1.0 op_sel_hi:[1,0]
	s_nop 0
	v_rcp_f32_e32 v94, v91
	s_nop 0
	v_mul_f32_e32 v91, v156, v94
	v_rcp_f32_e32 v93, v90
	s_nop 0
	v_mul_f32_e32 v90, v92, v93
	v_pk_mul_f32 v[172:173], v[172:173], v[90:91]
	v_lshlrev_b32_e32 v90, 16, v157
	v_and_b32_e32 v91, 0xffff0000, v157
	v_mul_f32_e32 v156, 0xbfb8aa3b, v90
	v_mul_f32_e32 v157, 0xbfb8aa3b, v91
	v_exp_f32_e32 v156, v156
	v_exp_f32_e32 v157, v157
	v_cvt_pk_bf16_f32 v172, v172, v173
	v_pk_add_f32 v[156:157], v[156:157], 1.0 op_sel_hi:[1,0]
	s_nop 0
	v_rcp_f32_e32 v93, v157
	s_nop 0
	v_mul_f32_e32 v157, v91, v93
	v_rcp_f32_e32 v92, v156
	s_nop 0
	v_mul_f32_e32 v156, v90, v92
	v_pk_mul_f32 v[174:175], v[174:175], v[156:157]
	s_nop 0
	v_cvt_pk_bf16_f32 v173, v174, v175
	global_store_dwordx2 v[86:87], v[172:173], off offset:2048
	v_lshl_add_u64 v[86:87], v[86:87], 0, s[18:19]
	s_waitcnt vmcnt(15) lgkmcnt(2)
	v_lshlrev_b32_e32 v92, 16, v158
	v_and_b32_e32 v158, 0xffff0000, v158
	v_mul_f32_e32 v90, 0xbfb8aa3b, v92
	v_mul_f32_e32 v91, 0xbfb8aa3b, v158
	v_exp_f32_e32 v90, v90
	v_exp_f32_e32 v91, v91
	s_nop 0
	v_pk_add_f32 v[90:91], v[90:91], 1.0 op_sel_hi:[1,0]
	s_nop 0
	v_rcp_f32_e32 v94, v91
	s_nop 0
	v_mul_f32_e32 v91, v158, v94
	v_rcp_f32_e32 v93, v90
	s_nop 0
	v_mul_f32_e32 v90, v92, v93
	v_pk_mul_f32 v[176:177], v[176:177], v[90:91]
	v_lshlrev_b32_e32 v90, 16, v159
	v_and_b32_e32 v91, 0xffff0000, v159
	v_mul_f32_e32 v158, 0xbfb8aa3b, v90
	v_mul_f32_e32 v159, 0xbfb8aa3b, v91
	v_exp_f32_e32 v158, v158
	v_exp_f32_e32 v159, v159
	v_cvt_pk_bf16_f32 v176, v176, v177
	v_pk_add_f32 v[158:159], v[158:159], 1.0 op_sel_hi:[1,0]
	s_nop 0
	v_rcp_f32_e32 v93, v159
	s_nop 0
	v_mul_f32_e32 v159, v91, v93
	v_rcp_f32_e32 v92, v158
	s_nop 0
	v_mul_f32_e32 v158, v90, v92
	v_pk_mul_f32 v[178:179], v[178:179], v[158:159]
	s_nop 0
	v_cvt_pk_bf16_f32 v177, v178, v179
	global_store_dwordx2 v[86:87], v[176:177], off offset:2048
	v_lshl_add_u64 v[86:87], v[86:87], 0, s[18:19]
	s_waitcnt vmcnt(15) lgkmcnt(1)
	v_lshlrev_b32_e32 v92, 16, v160
	v_and_b32_e32 v160, 0xffff0000, v160
	v_mul_f32_e32 v90, 0xbfb8aa3b, v92
	v_mul_f32_e32 v91, 0xbfb8aa3b, v160
	v_exp_f32_e32 v90, v90
	v_exp_f32_e32 v91, v91
	s_nop 0
	v_pk_add_f32 v[90:91], v[90:91], 1.0 op_sel_hi:[1,0]
	s_nop 0
	v_rcp_f32_e32 v94, v91
	s_nop 0
	v_mul_f32_e32 v91, v160, v94
	v_rcp_f32_e32 v93, v90
	s_nop 0
	v_mul_f32_e32 v90, v92, v93
	v_pk_mul_f32 v[180:181], v[180:181], v[90:91]
	v_lshlrev_b32_e32 v90, 16, v161
	v_and_b32_e32 v91, 0xffff0000, v161
	v_mul_f32_e32 v160, 0xbfb8aa3b, v90
	v_mul_f32_e32 v161, 0xbfb8aa3b, v91
	v_exp_f32_e32 v160, v160
	v_exp_f32_e32 v161, v161
	v_cvt_pk_bf16_f32 v180, v180, v181
	v_pk_add_f32 v[160:161], v[160:161], 1.0 op_sel_hi:[1,0]
	s_nop 0
	v_rcp_f32_e32 v93, v161
	s_nop 0
	v_mul_f32_e32 v161, v91, v93
	v_rcp_f32_e32 v92, v160
	s_nop 0
	v_mul_f32_e32 v160, v90, v92
	v_pk_mul_f32 v[182:183], v[182:183], v[160:161]
	s_nop 0
	v_cvt_pk_bf16_f32 v181, v182, v183
	global_store_dwordx2 v[86:87], v[180:181], off offset:2048
	v_lshl_add_u64 v[86:87], v[86:87], 0, s[18:19]
	s_waitcnt vmcnt(15) lgkmcnt(0)
	v_lshlrev_b32_e32 v92, 16, v162
	v_and_b32_e32 v162, 0xffff0000, v162
	v_mul_f32_e32 v90, 0xbfb8aa3b, v92
	v_mul_f32_e32 v91, 0xbfb8aa3b, v162
	v_exp_f32_e32 v90, v90
	v_exp_f32_e32 v91, v91
	s_nop 0
	v_pk_add_f32 v[90:91], v[90:91], 1.0 op_sel_hi:[1,0]
	s_nop 0
	v_rcp_f32_e32 v94, v91
	s_nop 0
	v_mul_f32_e32 v91, v162, v94
	v_rcp_f32_e32 v93, v90
	s_nop 0
	v_mul_f32_e32 v90, v92, v93
	v_pk_mul_f32 v[184:185], v[184:185], v[90:91]
	v_lshlrev_b32_e32 v90, 16, v163
	v_and_b32_e32 v91, 0xffff0000, v163
	v_mul_f32_e32 v162, 0xbfb8aa3b, v90
	v_mul_f32_e32 v163, 0xbfb8aa3b, v91
	v_exp_f32_e32 v162, v162
	v_exp_f32_e32 v163, v163
	v_cvt_pk_bf16_f32 v184, v184, v185
	v_pk_add_f32 v[162:163], v[162:163], 1.0 op_sel_hi:[1,0]
	s_nop 0
	v_rcp_f32_e32 v93, v163
	s_nop 0
	v_mul_f32_e32 v163, v91, v93
	v_rcp_f32_e32 v92, v162
	s_nop 0
	v_mul_f32_e32 v162, v90, v92
	v_pk_mul_f32 v[186:187], v[186:187], v[162:163]
	s_nop 0
	v_cvt_pk_bf16_f32 v185, v186, v187
	global_store_dwordx2 v[86:87], v[184:185], off offset:2048
	v_lshl_add_u64 v[86:87], v[86:87], 0, s[18:19]
	s_barrier
	s_branch .LBB0_173
